# v119 + non-temporal hint (nt) on the read-once x loads of phase 0
# speedup vs baseline: 1.0284x; 1.0158x over previous
.LBB0_25:
	v_add_u32_e32 v2, 0xffffc000, v0
	v_lshlrev_b64 v[24:25], 12, v[2:3]
	v_lshl_add_u64 v[24:25], s[10:11], 0, v[24:25]
	v_cmp_gt_i32_e64 s[6:7], s5, v0
	v_mov_b32_e32 v11, v3
	s_nop 0
	v_cndmask_b32_e64 v25, v25, v7, s[6:7]
	v_cndmask_b32_e64 v24, v24, v6, s[6:7]
	v_lshl_add_u64 v[36:37], v[24:25], 0, v[10:11]
	global_load_dwordx4 v[24:27], v[36:37], off nt
	global_load_dwordx4 v[28:31], v[36:37], off offset:1024 nt
	global_load_dwordx4 v[32:35], v[36:37], off offset:2048 nt
	global_load_dwordx4 v[36:39], v[36:37], off offset:3072 nt
	v_cmp_lt_i32_e64 s[6:7], v16, v17
	s_waitcnt vmcnt(3)
	v_cvt_pk_bf16_f32 v40, v24, v25
	v_cvt_pk_bf16_f32 v41, v26, v27
	global_store_dwordx2 v[12:13], v[40:41], off
	v_mul_f32_e32 v11, v25, v25
	v_fmac_f32_e32 v11, v24, v24
	v_fmac_f32_e32 v11, v26, v26
	v_fmac_f32_e32 v11, v27, v27
	v_cndmask_b32_e64 v2, v15, v16, s[6:7]
	v_lshlrev_b32_e32 v2, 2, v2
	v_cmp_lt_i32_e64 s[6:7], v18, v17
	s_waitcnt vmcnt(3)
	v_cvt_pk_bf16_f32 v42, v28, v29
	v_cvt_pk_bf16_f32 v43, v30, v31
	global_store_dwordx2 v[12:13], v[42:43], off offset:512
	s_waitcnt lgkmcnt(0)
	v_mul_f32_e32 v23, v29, v29
	v_fmac_f32_e32 v23, v28, v28
	v_fmac_f32_e32 v23, v30, v30
	v_fmac_f32_e32 v23, v31, v31
	v_add_f32_e32 v11, v11, v23
	s_waitcnt vmcnt(3)
	v_cvt_pk_bf16_f32 v44, v32, v33
	v_cvt_pk_bf16_f32 v45, v34, v35
	global_store_dwordx2 v[12:13], v[44:45], off offset:1024
	v_mul_f32_e32 v23, v33, v33
	v_fmac_f32_e32 v23, v32, v32
	v_fmac_f32_e32 v23, v34, v34
	v_fmac_f32_e32 v23, v35, v35
	v_add_f32_e32 v11, v11, v23
	s_waitcnt vmcnt(3)
	v_mul_f32_e32 v23, v37, v37
	v_fmac_f32_e32 v23, v36, v36
	v_fmac_f32_e32 v23, v38, v38
	v_fmac_f32_e32 v23, v39, v39
	v_add_f32_e32 v11, v11, v23
	v_cvt_pk_bf16_f32 v24, v36, v37
	v_cvt_pk_bf16_f32 v25, v38, v39
	global_store_dwordx2 v[12:13], v[24:25], off offset:1536
	s_mov_b64 s[6:7], s[24:25]
	s_nop 1
	v_add_f32_dpp v11, v11, v11 quad_perm:[1,0,3,2] row_mask:0xf bank_mask:0xf bound_ctrl:1
	s_nop 1
	v_add_f32_dpp v11, v11, v11 quad_perm:[2,3,0,1] row_mask:0xf bank_mask:0xf bound_ctrl:1
	s_nop 1
	v_add_f32_dpp v11, v11, v11 row_half_mirror row_mask:0xf bank_mask:0xf bound_ctrl:1
	s_nop 1
	v_add_f32_dpp v11, v11, v11 row_mirror row_mask:0xf bank_mask:0xf bound_ctrl:1
	v_mov_b32_e32 v23, v11
	s_nop 1
	v_permlane16_swap_b32_e32 v11, v23
	s_nop 0
	v_add_f32_e32 v11, v11, v23
	v_mov_b32_e32 v23, v11
	s_nop 1
	v_permlane32_swap_b32_e32 v11, v23
	s_nop 0
	v_add_f32_e32 v11, v11, v23
	v_mov_b32_e32 v23, 0
	s_and_saveexec_b64 s[28:29], vcc
	s_cbranch_execz .LBB0_27
	s_waitcnt lgkmcnt(0)
	v_add_f32_e32 v2, v11, v23
	v_fmamk_f32 v2, v2, 0x3a800000, v1
	v_mul_f32_e32 v11, 0x4b800000, v2
	v_cmp_gt_f32_e64 s[6:7], s17, v2
	s_nop 1
	v_cndmask_b32_e64 v2, v2, v11, s[6:7]
	v_rsq_f32_e32 v2, v2
	s_nop 0
	v_mul_f32_e32 v11, 0x45800000, v2
	v_cndmask_b32_e64 v2, v2, v11, s[6:7]
	s_or_b64 s[6:7], s[24:25], exec
